# phase0 weight transposes: tiles A/B of each 4-tile group load with 16 independent masked loads (scalar base + running 32-bit offset) instead of pairwise-waited loads with register-array copies
# speedup vs baseline: 1.0067x; 1.0067x over previous
.LBB0_95:
	s_or_b64 exec, exec, s[58:59]
	s_lshl_b32 s4, s67, 6
	v_cmp_lt_i32_e32 vcc, -1, v50
	v_add_u32_e32 v36, s4, v56
	v_mul_lo_u32 v34, v36, s50
	v_add_lshl_u32 v34, v34, v50, 2
	s_lshl_b32 s100, s50, 4
	v_mov_b32_e32 v2, 0
	v_mov_b32_e32 v3, 0
	v_mov_b32_e32 v4, 0
	v_mov_b32_e32 v5, 0
	v_mov_b32_e32 v6, 0
	v_mov_b32_e32 v7, 0
	v_mov_b32_e32 v8, 0
	v_mov_b32_e32 v9, 0
	v_mov_b32_e32 v10, 0
	v_mov_b32_e32 v11, 0
	v_mov_b32_e32 v12, 0
	v_mov_b32_e32 v13, 0
	v_mov_b32_e32 v14, 0
	v_mov_b32_e32 v15, 0
	v_mov_b32_e32 v16, 0
	v_mov_b32_e32 v53, 0
	s_and_saveexec_b64 s[58:59], vcc
	s_cbranch_execz .Lp0_a_done
	global_load_dword v2, v34, s[56:57]
	v_add_u32_e32 v34, s100, v34
	global_load_dword v3, v34, s[56:57]
	v_add_u32_e32 v34, s100, v34
	global_load_dword v4, v34, s[56:57]
	v_add_u32_e32 v34, s100, v34
	global_load_dword v5, v34, s[56:57]
	v_add_u32_e32 v34, s100, v34
	global_load_dword v6, v34, s[56:57]
	v_add_u32_e32 v34, s100, v34
	global_load_dword v7, v34, s[56:57]
	v_add_u32_e32 v34, s100, v34
	global_load_dword v8, v34, s[56:57]
	v_add_u32_e32 v34, s100, v34
	global_load_dword v9, v34, s[56:57]
	v_add_u32_e32 v34, s100, v34
	global_load_dword v10, v34, s[56:57]
	v_add_u32_e32 v34, s100, v34
	global_load_dword v11, v34, s[56:57]
	v_add_u32_e32 v34, s100, v34
	global_load_dword v12, v34, s[56:57]
	v_add_u32_e32 v34, s100, v34
	global_load_dword v13, v34, s[56:57]
	v_add_u32_e32 v34, s100, v34
	global_load_dword v14, v34, s[56:57]
	v_add_u32_e32 v34, s100, v34
	global_load_dword v15, v34, s[56:57]
	v_add_u32_e32 v34, s100, v34
	global_load_dword v16, v34, s[56:57]
	v_add_u32_e32 v34, s100, v34
	global_load_dword v53, v34, s[56:57]
.Lp0_a_done:
	s_or_b64 exec, exec, s[58:59]
	s_lshl_b32 s27, s51, 6
	v_or_b32_e32 v50, s27, v1
	v_cmp_lt_i32_e32 vcc, s63, v50
	s_and_b64 s[54:55], s[54:55], vcc
	s_and_saveexec_b64 s[50:51], s[54:55]
	s_cbranch_execz .LBB0_133
	s_cmpk_gt_u32 s27, 0x1bff
	s_mov_b64 s[54:55], -1
	s_cbranch_scc0 .LBB0_130
	v_add_u32_e32 v17, 0xfffff200, v50
	v_cmp_gt_u32_e32 vcc, s33, v50
	s_mov_b64 s[54:55], 0
	s_nop 0
	v_cndmask_b32_e32 v17, -1, v17, vcc

.LBB0_133:
	s_or_b64 exec, exec, s[50:51]
	s_lshl_b32 s31, s66, 6
	v_cmp_lt_i32_e32 vcc, -1, v50
	v_add_u32_e32 v63, s31, v56
	v_mul_lo_u32 v54, v63, s38
	v_add_lshl_u32 v54, v54, v50, 2
	s_lshl_b32 s101, s38, 4
	v_mov_b32_e32 v18, 0
	v_mov_b32_e32 v19, 0
	v_mov_b32_e32 v20, 0
	v_mov_b32_e32 v21, 0
	v_mov_b32_e32 v22, 0
	v_mov_b32_e32 v23, 0
	v_mov_b32_e32 v24, 0
	v_mov_b32_e32 v25, 0
	v_mov_b32_e32 v26, 0
	v_mov_b32_e32 v27, 0
	v_mov_b32_e32 v28, 0
	v_mov_b32_e32 v29, 0
	v_mov_b32_e32 v30, 0
	v_mov_b32_e32 v17, 0
	v_mov_b32_e32 v32, 0
	v_mov_b32_e32 v31, 0
	s_and_saveexec_b64 s[50:51], vcc
	s_cbranch_execz .Lp0_b_done
	global_load_dword v18, v54, s[52:53]
	v_add_u32_e32 v54, s101, v54
	global_load_dword v19, v54, s[52:53]
	v_add_u32_e32 v54, s101, v54
	global_load_dword v20, v54, s[52:53]
	v_add_u32_e32 v54, s101, v54
	global_load_dword v21, v54, s[52:53]
	v_add_u32_e32 v54, s101, v54
	global_load_dword v22, v54, s[52:53]
	v_add_u32_e32 v54, s101, v54
	global_load_dword v23, v54, s[52:53]
	v_add_u32_e32 v54, s101, v54
	global_load_dword v24, v54, s[52:53]
	v_add_u32_e32 v54, s101, v54
	global_load_dword v25, v54, s[52:53]
	v_add_u32_e32 v54, s101, v54
	global_load_dword v26, v54, s[52:53]
	v_add_u32_e32 v54, s101, v54
	global_load_dword v27, v54, s[52:53]
	v_add_u32_e32 v54, s101, v54
	global_load_dword v28, v54, s[52:53]
	v_add_u32_e32 v54, s101, v54
	global_load_dword v29, v54, s[52:53]
	v_add_u32_e32 v54, s101, v54
	global_load_dword v30, v54, s[52:53]
	v_add_u32_e32 v54, s101, v54
	global_load_dword v17, v54, s[52:53]
	v_add_u32_e32 v54, s101, v54
	global_load_dword v32, v54, s[52:53]
	v_add_u32_e32 v54, s101, v54
	global_load_dword v31, v54, s[52:53]
